# baseline (speedup 1.0000x reference)
; __device__ __forceinline__ void attn_sb(const bf16* __restrict__ Qg  , const bf16* __restrict__ Kg, const bf16* __restrict__ Vg, int vts,
;                         bf16* __restrict__ Og, int qpos0, int nq, char* lds) {
;     ...
;     for (int k0s = ((qpos_w + 30) >> 5) << 5; k0s >= 0; k0s -= 32) {
;       bf16x8 kf[4], vf[4];
; #pragma unroll
;       for (int kk = 0; kk < 4; ++kk) kf[kk] = *reinterpret_cast<const bf16x8*>(Kg + (size_t)(k0s + j) * 1024 + kk * 16 + 8 * h);
; #pragma unroll
;       for (int ks = 0; ks < 2; ++ks) {
;         vf[ks] = *reinterpret_cast<const bf16x8*>(Vg + (size_t)j * vts + k0s + ks * 16 + 8 * h);
;         vf[2 + ks] = *reinterpret_cast<const bf16x8*>(Vg + (size_t)(32 + j) * vts + k0s + ks * 16 + 8 * h);
;       }
;       f32x16 S = {};
; #pragma unroll
;       for (int kk = 0; kk < 4; ++kk) S = __builtin_amdgcn_mfma_f32_32x32x16_bf16(kf[kk], qf[kk], S, 0, 0, 0);
;           const int thr = qpos_w + j - k0s - 4 * h;
;           float ls[16], lg[16];
; #pragma unroll
;           for (int r = 0; r < 16; ++r) {
;             const float z = S[r];
;             const float e = __builtin_amdgcn_exp2f(-fabsf(z));
;             const float sp = fmaxf(z, 0.f) + __builtin_amdgcn_logf(1.f + e);
;             const bool valid = ((r & 3) + 8 * (r >> 2)) < thr;
;             ls[r] = valid ? -sp : 0.f;
;             lg[r] = z - sp;
;           }
.LBB0_194:
	v_add_u32_e32 v0, v101, v90
	v_lshlrev_b64 v[34:35], 11, v[0:1]
	v_lshl_add_u64 v[74:75], v[84:85], 0, v[34:35]
	flat_load_dwordx4 v[34:37], v[74:75]
	flat_load_dwordx4 v[66:69], v[74:75] offset:32
	flat_load_dwordx4 v[70:73], v[74:75] offset:64
	flat_load_dwordx4 v[94:97], v[74:75] offset:96
	v_mov_b32_e32 v91, v1
	v_cmp_lt_i32_e64 s[14:15], 1, v103
	v_cmp_lt_i32_e64 s[18:19], 8, v103
	v_cmp_lt_i32_e32 vcc, 16, v103
	v_cmp_lt_i32_e64 s[8:9], 17, v103
	v_cmp_lt_i32_e64 s[12:13], 24, v103
	v_cmp_lt_i32_e64 s[26:27], 25, v103
	v_cmp_lt_i32_e64 s[28:29], 26, v103
	v_cmp_lt_i32_e64 s[34:35], 27, v103
	v_cmp_lt_i32_e64 s[30:31], 0, v103
	v_cmp_lt_i32_e64 s[10:11], 18, v103
	v_cmp_lt_i32_e64 s[20:21], 9, v103
	v_cmp_lt_i32_e64 s[22:23], 10, v103
	v_cmp_lt_i32_e64 s[24:25], 11, v103
	v_cmp_lt_i32_e64 s[36:37], 19, v103
	v_cmp_lt_i32_e64 s[16:17], 2, v103
	s_mov_b32 s0, 0xc2100000
	s_waitcnt vmcnt(0) lgkmcnt(0)
	v_mfma_f32_32x32x16_bf16 v[34:49], v[34:37], v[50:53], 0
	v_mfma_f32_32x32x16_bf16 v[34:49], v[66:69], v[54:57], v[34:49]
	v_lshlrev_b64 v[66:67], 1, v[90:91]
	v_lshl_add_u64 v[68:69], v[86:87], 0, v[66:67]
	v_lshl_add_u64 v[66:67], v[88:89], 0, v[66:67]
	v_mfma_f32_32x32x16_bf16 v[34:49], v[70:73], v[58:61], v[34:49]
	flat_load_dwordx4 v[78:81], v[68:69]
	flat_load_dwordx4 v[70:73], v[68:69] offset:32
	flat_load_dwordx4 v[74:77], v[66:67]
	s_nop 0
	flat_load_dwordx4 v[66:69], v[66:67] offset:32
	v_mfma_f32_32x32x16_bf16 v[34:49], v[94:97], v[62:65], v[34:49]
	s_nop 11
	v_exp_f32_e64 v0, -|v34|
	v_exp_f32_e64 v95, -|v35|
	v_exp_f32_e64 v96, -|v36|
	v_exp_f32_e64 v97, -|v37|
	v_exp_f32_e64 v99, -|v38|
	v_exp_f32_e64 v105, -|v39|
	v_exp_f32_e64 v107, -|v40|
	v_exp_f32_e64 v109, -|v41|
	v_exp_f32_e64 v111, -|v42|
	v_exp_f32_e64 v113, -|v43|
	v_exp_f32_e64 v115, -|v44|
	v_exp_f32_e64 v117, -|v45|
	v_exp_f32_e64 v119, -|v46|
	v_exp_f32_e64 v121, -|v47|
	v_exp_f32_e64 v123, -|v48|
	v_exp_f32_e64 v125, -|v49|
	v_max_f32_e32 v128, 0, v36
	v_max_f32_e32 v94, 0, v37
	v_add_f32_e32 v0, 1.0, v0
	v_add_f32_e32 v95, 1.0, v95
	v_add_f32_e32 v96, 1.0, v96
	v_add_f32_e32 v97, 1.0, v97
	v_add_f32_e32 v98, 1.0, v99
	v_add_f32_e32 v99, 1.0, v105
	v_add_f32_e32 v105, 1.0, v107
	v_add_f32_e32 v107, 1.0, v109
	v_add_f32_e32 v109, 1.0, v111
	v_add_f32_e32 v111, 1.0, v113
	v_add_f32_e32 v113, 1.0, v115
	v_add_f32_e32 v115, 1.0, v117
	v_add_f32_e32 v117, 1.0, v119
	v_add_f32_e32 v119, 1.0, v121
	v_add_f32_e32 v121, 1.0, v123
	v_add_f32_e32 v123, 1.0, v125
	v_log_f32_e32 v0, v0
	v_log_f32_e32 v95, v95
	v_log_f32_e32 v125, v96
	v_log_f32_e32 v96, v97
	v_log_f32_e32 v97, v98
	v_log_f32_e32 v99, v99
	v_log_f32_e32 v109, v109
	v_log_f32_e32 v111, v111
	v_log_f32_e32 v98, v115
	v_log_f32_e32 v115, v117
	v_log_f32_e32 v117, v119
	v_log_f32_e32 v119, v121
	v_log_f32_e32 v121, v123
	v_log_f32_e32 v105, v105
	v_log_f32_e32 v107, v107
	v_log_f32_e32 v113, v113
	v_max_f32_e32 v91, 0, v34
	v_max_f32_e32 v127, 0, v35
	v_max_f32_e32 v104, 0, v38
	v_max_f32_e32 v106, 0, v39
	v_max_f32_e32 v112, 0, v42
	v_max_f32_e32 v114, 0, v43
	v_max_f32_e32 v92, 0, v45
	v_max_f32_e32 v118, 0, v46
	v_max_f32_e32 v120, 0, v47
	v_max_f32_e32 v122, 0, v48
	v_max_f32_e32 v124, 0, v49
	v_max_f32_e32 v108, 0, v40
	v_max_f32_e32 v110, 0, v41
	v_max_f32_e32 v116, 0, v44
	v_add_f32_e32 v0, v91, v0
	v_add_f32_e32 v95, v127, v95
	v_add_f32_e32 v123, v128, v125
	v_add_f32_e32 v97, v104, v97
	v_add_f32_e32 v99, v106, v99
	v_add_f32_e32 v127, v112, v109
	v_add_f32_e32 v128, v114, v111
	v_add_f32_e32 v115, v118, v115
	v_add_f32_e32 v117, v120, v117
	v_add_f32_e32 v118, v122, v119
	v_add_f32_e32 v119, v124, v121
	v_add_f32_e32 v125, v108, v105
	v_add_f32_e32 v126, v110, v107
	v_add_f32_e32 v116, v116, v113
	v_cndmask_b32_e64 v120, 0, -v0, s[30:31]
	v_sub_f32_e32 v91, v34, v0
	v_cndmask_b32_e64 v104, 0, -v95, s[14:15]
	v_sub_f32_e32 v105, v35, v95
	v_cndmask_b32_e64 v34, 0, -v97, s[18:19]
	v_sub_f32_e32 v108, v38, v97
	v_sub_f32_e32 v110, v39, v99
	v_cndmask_b32_e64 v35, 0, -v127, vcc
	v_sub_f32_e32 v0, v42, v127
	v_cndmask_b32_e64 v42, 0, -v128, s[8:9]
	v_cndmask_b32_e64 v38, 0, -v115, s[12:13]
	v_sub_f32_e32 v39, v46, v115
	v_cndmask_b32_e64 v46, 0, -v117, s[26:27]
	v_cndmask_b32_e64 v95, 0, -v118, s[28:29]
	v_cndmask_b32_e64 v97, 0, -v119, s[34:35]
	v_sub_f32_e32 v107, v36, v123
	v_sub_f32_e32 v114, v41, v126
	v_sub_f32_e32 v36, v43, v128
	v_cndmask_b32_e64 v43, 0, -v116, s[10:11]
; __device__ __forceinline__ void attn_sb(const bf16* __restrict__ Qg  , const bf16* __restrict__ Kg, const bf16* __restrict__ Vg, int vts,
;                         bf16* __restrict__ Og, int qpos0, int nq, char* lds) {
;     ...
;           float both[4], extra[4];
; #pragma unroll
;           for (int g = 0; g < 4; ++g) {
;             float G = (ls[4 * g] + ls[4 * g + 1]) + (ls[4 * g + 2] + ls[4 * g + 3]);
;             auto rr = __builtin_amdgcn_permlane32_swap(__float_as_uint(G), __float_as_uint(G), false, false);
;             float lo = __uint_as_float(rr[0]), hi = __uint_as_float(rr[1]);
;             both[g] = lo + hi; extra[g] = hsel * hi;
;           }
;           float T3 = R, T2 = T3 + both[3], T1 = T2 + both[2], T0 = T1 + both[1];
;           R = T0 + both[0];
;           float Tg[4] = {T0, T1, T2, T3};
;           float wv[16];
; #pragma unroll
;           for (int g = 0; g < 4; ++g) {
;             float c3 = Tg[g] + extra[g];
;             float c2 = c3 + ls[4 * g + 3];
;             float c1 = c2 + ls[4 * g + 2];
;             float c0 = c1 + ls[4 * g + 1];
;             float cc[4] = {c0, c1, c2, c3};
; #pragma unroll
;             for (int i = 0; i < 4; ++i) {
;               const int r = 4 * g + i;
;               const bool valid = ((r & 3) + 8 * (r >> 2)) < thr;
;               const float e2 = __builtin_amdgcn_exp2f(lg[r] + cc[i]);
;               wv[r] = valid ? e2 : 0.f;
;             }
;           }
;           bf16x8 pf[2];
; #pragma unroll
;       for (int ks = 0; ks < 2; ++ks) {
;         u32x4 pw = {cvtpk(wv[8 * ks], wv[8 * ks + 1]), cvtpk(wv[8 * ks + 2], wv[8 * ks + 3]), cvtpk(wv[8 * ks + 4], wv[8 * ks + 5]), cvtpk(wv[8 * ks + 6], wv[8 * ks + 7])};
;         pf[ks] = __builtin_bit_cast(bf16x8, pw);
;       }
; #pragma unroll
;       for (int ks = 0; ks < 2; ++ks) {
;         O0 = __builtin_amdgcn_mfma_f32_32x32x16_bf16(vf[ks], pf[ks], O0, 0, 0, 0);
;         O1 = __builtin_amdgcn_mfma_f32_32x32x16_bf16(vf[2 + ks], pf[ks], O1, 0, 0, 0);
;       }
;       if (__all(R <= SB_CUT)) break;
	v_sub_f32_e32 v44, v44, v116
	v_add_f32_e32 v116, v35, v42
	v_add_f32_e32 v35, v38, v46
	v_add_f32_e32 v41, v95, v97
	v_add_f32_e32 v35, v35, v41
	v_sub_f32_e32 v47, v47, v117
	v_mov_b32_e32 v117, v35
	v_cndmask_b32_e64 v109, 0, -v99, s[20:21]
	v_cndmask_b32_e64 v111, 0, -v125, s[22:23]
	v_cndmask_b32_e64 v113, 0, -v126, s[24:25]
	v_permlane32_swap_b32_e32 v35, v117
	v_sub_f32_e32 v112, v40, v125
	v_add_f32_e32 v34, v34, v109
	v_add_f32_e32 v40, v111, v113
	v_add_f32_e32 v99, v35, v117
	v_add_f32_e32 v38, v34, v40
	v_pk_add_f32 v[40:41], v[92:93], v[98:99]
	v_sub_f32_e32 v49, v49, v119
	v_fmac_f32_e32 v93, v102, v117
	v_cndmask_b32_e64 v92, 0, -v40, s[36:37]
	v_sub_f32_e32 v48, v48, v118
	v_sub_f32_e32 v40, v45, v40
	v_add_f32_e32 v45, v97, v93
	v_add_f32_e32 v49, v49, v93
	v_add_f32_e32 v93, v43, v92
	v_add_f32_e32 v95, v95, v45
	v_add_f32_e32 v45, v48, v45
	v_exp_f32_e32 v48, v49
	v_add_f32_e32 v49, v116, v93
	v_add_f32_e32 v46, v46, v95
	v_add_f32_e32 v47, v47, v95
	v_mov_b32_e32 v93, v49
	v_mov_b32_e32 v34, v38
	v_add_f32_e32 v39, v39, v46
	v_exp_f32_e32 v46, v47
	v_permlane32_swap_b32_e32 v49, v93
	v_permlane32_swap_b32_e32 v38, v34
	v_mov_b32_e32 v35, v41
	v_exp_f32_e32 v47, v39
	v_add_f32_e32 v39, v49, v93
	v_fma_f32 v41, v102, v93, v41
	v_pk_add_f32 v[38:39], v[38:39], v[34:35]
	v_add_f32_e32 v35, v92, v41
	v_mov_b32_e32 v95, v38
	v_mov_b32_e32 v97, v39
	v_add_f32_e32 v40, v40, v41
	v_fmac_f32_e32 v39, v102, v34
	v_add_f32_e32 v43, v43, v35
	v_add_f32_e32 v44, v44, v35
	v_cndmask_b32_e64 v46, 0, v46, s[26:27]
	v_pk_add_f32 v[34:35], v[94:95], v[96:97]
	v_cmp_lt_i32_e64 s[26:27], 3, v103
	v_cndmask_b32_e64 v106, 0, -v123, s[16:17]
	v_exp_f32_e32 v49, v40
	v_add_f32_e32 v38, v113, v39
	v_add_f32_e32 v39, v114, v39
	v_cndmask_b32_e64 v40, 0, -v34, s[26:27]
	v_add_f32_e32 v115, v120, v104
	v_sub_f32_e32 v34, v37, v34
	v_add_f32_e32 v37, v111, v38
	v_add_f32_e32 v38, v112, v38
	v_exp_f32_e32 v39, v39
	v_add_f32_e32 v41, v106, v40
	v_add_f32_e32 v92, v109, v37
	v_exp_f32_e32 v38, v38
	v_add_f32_e32 v93, v115, v41
	v_add_f32_e32 v41, v108, v92
	v_mov_b32_e32 v92, v93
	v_exp_f32_e32 v41, v41
	s_nop 0
	v_permlane32_swap_b32_e32 v93, v92
	v_cndmask_b32_e64 v94, 0, v39, s[24:25]
	v_fma_f32 v39, v102, v92, v35
	v_cndmask_b32_e64 v95, 0, v38, s[22:23]
	v_add_f32_e32 v38, v40, v39
	v_add_f32_e32 v34, v34, v39
	v_add_f32_e32 v39, v106, v38
	v_cndmask_b32_e64 v40, 0, v41, s[18:19]
	v_add_f32_e32 v41, v104, v39
	v_add_f32_e32 v38, v107, v38
	v_add_f32_e32 v39, v105, v39
	v_add_f32_e32 v41, v91, v41
	v_add_f32_e32 v37, v110, v37
	v_exp_f32_e32 v38, v38
	v_exp_f32_e32 v39, v39
	v_exp_f32_e32 v41, v41
	v_exp_f32_e32 v37, v37
	v_exp_f32_e32 v34, v34
	v_cndmask_b32_e64 v91, 0, v38, s[16:17]
	v_cndmask_b32_e64 v38, 0, v39, s[14:15]
	v_cndmask_b32_e64 v39, 0, v41, s[30:31]
	v_add_f32_e32 v42, v42, v43
	v_cndmask_b32_e64 v37, 0, v37, s[20:21]
	v_cndmask_b32_e64 v34, 0, v34, s[26:27]
	v_cvt_pk_bf16_f32 v38, v39, v38
	v_cvt_pk_bf16_f32 v39, v91, v34
	v_cvt_pk_bf16_f32 v40, v40, v37
	v_cvt_pk_bf16_f32 v41, v95, v94
	v_add_f32_e32 v0, v0, v42
	s_waitcnt vmcnt(0) lgkmcnt(0)
	v_mfma_f32_32x32x16_bf16 v[2:17], v[78:81], v[38:41], v[2:17]
	v_add_f32_e32 v34, v36, v43
	v_exp_f32_e32 v0, v0
	v_exp_f32_e32 v36, v44
	v_exp_f32_e32 v34, v34
	v_exp_f32_e32 v45, v45
	v_cndmask_b32_e32 v0, 0, v0, vcc
	v_cndmask_b32_e64 v37, 0, v49, s[36:37]
	v_mfma_f32_32x32x16_bf16 v[18:33], v[74:77], v[38:41], v[18:33]
	v_cndmask_b32_e64 v38, 0, v36, s[10:11]
	v_cndmask_b32_e64 v34, 0, v34, s[8:9]
	v_cvt_pk_bf16_f32 v36, v0, v34
	v_subrev_u32_e32 v0, 32, v90
	v_cndmask_b32_e64 v48, 0, v48, s[34:35]
	v_cndmask_b32_e64 v45, 0, v45, s[28:29]
	v_cndmask_b32_e64 v43, 0, v47, s[12:13]
	v_cvt_pk_bf16_f32 v37, v38, v37
	v_cvt_pk_bf16_f32 v38, v43, v46
	v_cvt_pk_bf16_f32 v39, v45, v48
	v_cmp_eq_u32_e32 vcc, 0, v90
	v_mfma_f32_32x32x16_bf16 v[2:17], v[70:73], v[36:39], v[2:17]
	v_mov_b32_e32 v90, v0
	v_add_f32_e32 v0, v93, v92
	v_add_f32_e32 v93, v0, v35
	v_cmp_ge_f32_e64 s[8:9], s0, v93
	s_cmp_eq_u64 s[8:9], exec
	s_cselect_b64 s[0:1], -1, 0
	s_or_b64 s[0:1], vcc, s[0:1]
	v_mfma_f32_32x32x16_bf16 v[18:33], v[66:69], v[36:39], v[18:33]
	s_and_b64 s[0:1], exec, s[0:1]
	s_or_b64 s[4:5], s[0:1], s[4:5]
	v_add_u32_e32 v103, 32, v103
	s_andn2_b64 exec, exec, s[4:5]
	s_cbranch_execnz .LBB0_194
	s_or_b64 exec, exec, s[4:5]
	v_mov_b32_e32 v0, v100
